# MFMA order variant n,k,m (srcA fragment held for 4 consecutive MFMAs) + SwiGLU epilogue rewrite
# baseline (speedup 1.0000x reference)
.LBB0_32:
	s_add_u32 s28, s54, 0xfff80080
	s_addc_u32 s29, s55, -1
	s_add_i32 s30, 0, 0x10000
	s_cmp_eq_u32 s27, 28
	s_cselect_b32 s79, s13, s29
	s_cselect_b32 s78, s16, s28
	s_cselect_b32 s69, s9, s26
	s_cselect_b32 s68, s24, s25
	s_add_i32 s31, 0, 0x14000
	v_add_u32_e32 v142, s30, v184
	v_add_u32_e32 v172, s31, v184
	ds_read_b128 v[130:133], v142
	ds_read_b128 v[134:137], v142 offset:1024
	ds_read_b128 v[138:141], v142 offset:2048
	ds_read_b128 v[142:145], v142 offset:3072
	ds_read_b128 v[146:149], v172
	ds_read_b128 v[150:153], v172 offset:1024
	ds_read_b128 v[154:157], v172 offset:2048
	ds_read_b128 v[172:175], v172 offset:3072
	v_lshl_add_u64 v[212:213], s[54:55], 0, v[166:167]
	s_add_i32 m0, s42, 0xc000
	ds_read_b128 v[176:179], v186
	ds_read_b128 v[180:183], v186 offset:1024
	ds_read_b128 v[188:191], v186 offset:2048
	ds_read_b128 v[192:195], v186 offset:3072
	ds_read_b128 v[196:199], v186 offset:4096
	ds_read_b128 v[200:203], v186 offset:5120
	ds_read_b128 v[204:207], v186 offset:6144
	ds_read_b128 v[208:211], v186 offset:7168
	global_load_lds_dwordx4 v[212:213], off
	v_lshl_add_u64 v[212:213], s[54:55], 0, v[168:169]
	s_add_i32 m0, s42, 0xe000
	s_nop 0
	global_load_lds_dwordx4 v[212:213], off
	s_waitcnt vmcnt(8)
	s_waitcnt lgkmcnt(0)
	s_barrier
	s_setprio 1
	s_waitcnt lgkmcnt(0)
	v_mfma_f32_16x16x32_bf16 v[126:129], v[130:133], v[176:179], v[126:129]
	v_mfma_f32_16x16x32_bf16 v[110:113], v[130:133], v[188:191], v[110:113]
	v_mfma_f32_16x16x32_bf16 v[94:97], v[130:133], v[196:199], v[94:97]
	v_mfma_f32_16x16x32_bf16 v[78:81], v[130:133], v[204:207], v[78:81]
	v_mfma_f32_16x16x32_bf16 v[126:129], v[134:137], v[180:183], v[126:129]
	v_mfma_f32_16x16x32_bf16 v[110:113], v[134:137], v[192:195], v[110:113]
	v_mfma_f32_16x16x32_bf16 v[94:97], v[134:137], v[200:203], v[94:97]
	v_mfma_f32_16x16x32_bf16 v[78:81], v[134:137], v[208:211], v[78:81]
	v_mfma_f32_16x16x32_bf16 v[122:125], v[138:141], v[176:179], v[122:125]
	v_mfma_f32_16x16x32_bf16 v[106:109], v[138:141], v[188:191], v[106:109]
	v_mfma_f32_16x16x32_bf16 v[90:93], v[138:141], v[196:199], v[90:93]
	v_mfma_f32_16x16x32_bf16 v[74:77], v[138:141], v[204:207], v[74:77]
	v_mfma_f32_16x16x32_bf16 v[122:125], v[142:145], v[180:183], v[122:125]
	v_mfma_f32_16x16x32_bf16 v[106:109], v[142:145], v[192:195], v[106:109]
	v_mfma_f32_16x16x32_bf16 v[90:93], v[142:145], v[200:203], v[90:93]
	v_mfma_f32_16x16x32_bf16 v[74:77], v[142:145], v[208:211], v[74:77]
	s_setprio 0
	s_setprio 1
	v_mfma_f32_16x16x32_bf16 v[118:121], v[146:149], v[176:179], v[118:121]
	v_mfma_f32_16x16x32_bf16 v[102:105], v[146:149], v[188:191], v[102:105]
	v_mfma_f32_16x16x32_bf16 v[86:89], v[146:149], v[196:199], v[86:89]
	v_mfma_f32_16x16x32_bf16 v[70:73], v[146:149], v[204:207], v[70:73]
	v_mfma_f32_16x16x32_bf16 v[118:121], v[150:153], v[180:183], v[118:121]
	v_mfma_f32_16x16x32_bf16 v[102:105], v[150:153], v[192:195], v[102:105]
	v_mfma_f32_16x16x32_bf16 v[86:89], v[150:153], v[200:203], v[86:89]
	v_mfma_f32_16x16x32_bf16 v[70:73], v[150:153], v[208:211], v[70:73]
	v_mfma_f32_16x16x32_bf16 v[114:117], v[154:157], v[176:179], v[114:117]
	v_mfma_f32_16x16x32_bf16 v[98:101], v[154:157], v[188:191], v[98:101]
	v_mfma_f32_16x16x32_bf16 v[82:85], v[154:157], v[196:199], v[82:85]
	v_mfma_f32_16x16x32_bf16 v[66:69], v[154:157], v[204:207], v[66:69]
	v_mfma_f32_16x16x32_bf16 v[114:117], v[172:175], v[180:183], v[114:117]
	v_mfma_f32_16x16x32_bf16 v[98:101], v[172:175], v[192:195], v[98:101]
	v_mfma_f32_16x16x32_bf16 v[82:85], v[172:175], v[200:203], v[82:85]
	v_mfma_f32_16x16x32_bf16 v[66:69], v[172:175], v[208:211], v[66:69]
	s_setprio 0
	s_barrier
	s_add_i32 s28, s30, s11
	v_lshl_add_u64 v[212:213], s[68:69], 0, v[160:161]
	s_mov_b32 m0, s28
	ds_read_b128 v[176:179], v186 offset:16384
	ds_read_b128 v[180:183], v186 offset:17408
	ds_read_b128 v[188:191], v186 offset:18432
	ds_read_b128 v[192:195], v186 offset:19456
	ds_read_b128 v[196:199], v186 offset:20480
	ds_read_b128 v[200:203], v186 offset:21504
	ds_read_b128 v[204:207], v186 offset:22528
	ds_read_b128 v[208:211], v186 offset:23552
	global_load_lds_dwordx4 v[212:213], off
	s_add_i32 m0, s28, 0x2000
	s_add_u32 s28, s68, 0x80000
	v_lshl_add_u64 v[232:233], s[68:69], 0, v[164:165]
	s_addc_u32 s29, s69, 0
	s_add_i32 s30, s31, s11
	global_load_lds_dwordx4 v[232:233], off
	v_lshl_add_u64 v[234:235], s[28:29], 0, v[160:161]
	s_mov_b32 m0, s30
	v_lshl_add_u64 v[236:237], s[78:79], 0, v[162:163]
	global_load_lds_dwordx4 v[234:235], off
	v_lshl_add_u64 v[234:235], s[28:29], 0, v[164:165]
	s_add_i32 m0, s30, 0x2000
	s_nop 0
	global_load_lds_dwordx4 v[234:235], off
	v_lshl_add_u64 v[234:235], s[78:79], 0, v[158:159]
	s_mov_b32 m0, s42
	s_nop 0
	global_load_lds_dwordx4 v[234:235], off
	s_mov_b32 m0, s57
	s_nop 0
	global_load_lds_dwordx4 v[236:237], off
	s_waitcnt vmcnt(8)
	s_waitcnt lgkmcnt(0)
	s_barrier
	s_setprio 1
	s_waitcnt lgkmcnt(0)
	v_mfma_f32_16x16x32_bf16 v[62:65], v[130:133], v[176:179], v[62:65]
	v_mfma_f32_16x16x32_bf16 v[46:49], v[130:133], v[188:191], v[46:49]
	v_mfma_f32_16x16x32_bf16 v[30:33], v[130:133], v[196:199], v[30:33]
	v_mfma_f32_16x16x32_bf16 v[14:17], v[130:133], v[204:207], v[14:17]
	v_mfma_f32_16x16x32_bf16 v[62:65], v[134:137], v[180:183], v[62:65]
	v_mfma_f32_16x16x32_bf16 v[46:49], v[134:137], v[192:195], v[46:49]
	v_mfma_f32_16x16x32_bf16 v[30:33], v[134:137], v[200:203], v[30:33]
	v_mfma_f32_16x16x32_bf16 v[14:17], v[134:137], v[208:211], v[14:17]
	v_mfma_f32_16x16x32_bf16 v[58:61], v[138:141], v[176:179], v[58:61]
	v_mfma_f32_16x16x32_bf16 v[42:45], v[138:141], v[188:191], v[42:45]
	v_mfma_f32_16x16x32_bf16 v[26:29], v[138:141], v[196:199], v[26:29]
	v_mfma_f32_16x16x32_bf16 v[10:13], v[138:141], v[204:207], v[10:13]
	v_mfma_f32_16x16x32_bf16 v[58:61], v[142:145], v[180:183], v[58:61]
	v_mfma_f32_16x16x32_bf16 v[42:45], v[142:145], v[192:195], v[42:45]
	v_mfma_f32_16x16x32_bf16 v[26:29], v[142:145], v[200:203], v[26:29]
	v_mfma_f32_16x16x32_bf16 v[10:13], v[142:145], v[208:211], v[10:13]
	s_setprio 0
	s_setprio 1
	v_mfma_f32_16x16x32_bf16 v[54:57], v[146:149], v[176:179], v[54:57]
	v_mfma_f32_16x16x32_bf16 v[38:41], v[146:149], v[188:191], v[38:41]
	v_mfma_f32_16x16x32_bf16 v[22:25], v[146:149], v[196:199], v[22:25]
	v_mfma_f32_16x16x32_bf16 v[6:9], v[146:149], v[204:207], v[6:9]
	v_mfma_f32_16x16x32_bf16 v[54:57], v[150:153], v[180:183], v[54:57]
	v_mfma_f32_16x16x32_bf16 v[38:41], v[150:153], v[192:195], v[38:41]
	v_mfma_f32_16x16x32_bf16 v[22:25], v[150:153], v[200:203], v[22:25]
	v_mfma_f32_16x16x32_bf16 v[6:9], v[150:153], v[208:211], v[6:9]
	v_mfma_f32_16x16x32_bf16 v[50:53], v[154:157], v[176:179], v[50:53]
	v_mfma_f32_16x16x32_bf16 v[34:37], v[154:157], v[188:191], v[34:37]
	v_mfma_f32_16x16x32_bf16 v[18:21], v[154:157], v[196:199], v[18:21]
	v_mfma_f32_16x16x32_bf16 v[2:5], v[154:157], v[204:207], v[2:5]
	v_mfma_f32_16x16x32_bf16 v[50:53], v[172:175], v[180:183], v[50:53]
	v_mfma_f32_16x16x32_bf16 v[34:37], v[172:175], v[192:195], v[34:37]
	v_mfma_f32_16x16x32_bf16 v[18:21], v[172:175], v[200:203], v[18:21]
	v_mfma_f32_16x16x32_bf16 v[2:5], v[172:175], v[208:211], v[2:5]
	s_setprio 0
	s_barrier
	s_add_i32 s30, 0, 0x18000
	s_add_i32 s31, 0, 0x1c000
	v_add_u32_e32 v142, s30, v184
	v_add_u32_e32 v172, s31, v184
	ds_read_b128 v[130:133], v142
	ds_read_b128 v[134:137], v142 offset:1024
	ds_read_b128 v[138:141], v142 offset:2048
	ds_read_b128 v[142:145], v142 offset:3072
	ds_read_b128 v[146:149], v172
	ds_read_b128 v[150:153], v172 offset:1024
	ds_read_b128 v[154:157], v172 offset:2048
	ds_read_b128 v[172:175], v172 offset:3072
	s_add_u32 s28, s78, 0x80000
	s_addc_u32 s29, s79, 0
	s_mov_b32 m0, s67
	v_lshl_add_u64 v[238:239], s[28:29], 0, v[158:159]
	ds_read_b128 v[176:179], v186 offset:32768
	ds_read_b128 v[180:183], v186 offset:33792
	ds_read_b128 v[188:191], v186 offset:34816
	ds_read_b128 v[192:195], v186 offset:35840
	ds_read_b128 v[196:199], v186 offset:36864
	ds_read_b128 v[200:203], v186 offset:37888
	ds_read_b128 v[204:207], v186 offset:38912
	ds_read_b128 v[208:211], v186 offset:39936
	global_load_lds_dwordx4 v[238:239], off
	v_lshl_add_u64 v[238:239], s[28:29], 0, v[162:163]
	s_mov_b32 m0, s72
	s_nop 0
	global_load_lds_dwordx4 v[238:239], off
	s_waitcnt vmcnt(8)
	s_waitcnt lgkmcnt(0)
	s_barrier
	s_setprio 1
	s_waitcnt lgkmcnt(0)
	v_mfma_f32_16x16x32_bf16 v[126:129], v[130:133], v[176:179], v[126:129]
	v_mfma_f32_16x16x32_bf16 v[110:113], v[130:133], v[188:191], v[110:113]
	v_mfma_f32_16x16x32_bf16 v[94:97], v[130:133], v[196:199], v[94:97]
	v_mfma_f32_16x16x32_bf16 v[78:81], v[130:133], v[204:207], v[78:81]
	v_mfma_f32_16x16x32_bf16 v[126:129], v[134:137], v[180:183], v[126:129]
	v_mfma_f32_16x16x32_bf16 v[110:113], v[134:137], v[192:195], v[110:113]
	v_mfma_f32_16x16x32_bf16 v[94:97], v[134:137], v[200:203], v[94:97]
	v_mfma_f32_16x16x32_bf16 v[78:81], v[134:137], v[208:211], v[78:81]
	v_mfma_f32_16x16x32_bf16 v[122:125], v[138:141], v[176:179], v[122:125]
	v_mfma_f32_16x16x32_bf16 v[106:109], v[138:141], v[188:191], v[106:109]
	v_mfma_f32_16x16x32_bf16 v[90:93], v[138:141], v[196:199], v[90:93]
	v_mfma_f32_16x16x32_bf16 v[74:77], v[138:141], v[204:207], v[74:77]
	v_mfma_f32_16x16x32_bf16 v[122:125], v[142:145], v[180:183], v[122:125]
	v_mfma_f32_16x16x32_bf16 v[106:109], v[142:145], v[192:195], v[106:109]
	v_mfma_f32_16x16x32_bf16 v[90:93], v[142:145], v[200:203], v[90:93]
	v_mfma_f32_16x16x32_bf16 v[74:77], v[142:145], v[208:211], v[74:77]
	s_setprio 0
	s_setprio 1
	v_mfma_f32_16x16x32_bf16 v[118:121], v[146:149], v[176:179], v[118:121]
	v_mfma_f32_16x16x32_bf16 v[102:105], v[146:149], v[188:191], v[102:105]
	v_mfma_f32_16x16x32_bf16 v[86:89], v[146:149], v[196:199], v[86:89]
	v_mfma_f32_16x16x32_bf16 v[70:73], v[146:149], v[204:207], v[70:73]
	v_mfma_f32_16x16x32_bf16 v[118:121], v[150:153], v[180:183], v[118:121]
	v_mfma_f32_16x16x32_bf16 v[102:105], v[150:153], v[192:195], v[102:105]
	v_mfma_f32_16x16x32_bf16 v[86:89], v[150:153], v[200:203], v[86:89]
	v_mfma_f32_16x16x32_bf16 v[70:73], v[150:153], v[208:211], v[70:73]
	v_mfma_f32_16x16x32_bf16 v[114:117], v[154:157], v[176:179], v[114:117]
	v_mfma_f32_16x16x32_bf16 v[98:101], v[154:157], v[188:191], v[98:101]
	v_mfma_f32_16x16x32_bf16 v[82:85], v[154:157], v[196:199], v[82:85]
	v_mfma_f32_16x16x32_bf16 v[66:69], v[154:157], v[204:207], v[66:69]
	v_mfma_f32_16x16x32_bf16 v[114:117], v[172:175], v[180:183], v[114:117]
	v_mfma_f32_16x16x32_bf16 v[98:101], v[172:175], v[192:195], v[98:101]
	v_mfma_f32_16x16x32_bf16 v[82:85], v[172:175], v[200:203], v[82:85]
	v_mfma_f32_16x16x32_bf16 v[66:69], v[172:175], v[208:211], v[66:69]
	s_setprio 0
	s_barrier
	s_add_i32 s28, s30, s11
	v_lshl_add_u64 v[212:213], v[212:213], 0, s[62:63]
	s_mov_b32 m0, s28
	ds_read_b128 v[176:179], v186 offset:49152
	ds_read_b128 v[180:183], v186 offset:50176
	ds_read_b128 v[188:191], v186 offset:51200
	ds_read_b128 v[192:195], v186 offset:52224
	ds_read_b128 v[196:199], v186 offset:53248
	ds_read_b128 v[200:203], v186 offset:54272
	ds_read_b128 v[204:207], v186 offset:55296
	ds_read_b128 v[208:211], v186 offset:56320
	global_load_lds_dwordx4 v[212:213], off
	s_add_i32 m0, s28, 0x2000
	s_add_u32 s28, s68, 0x80080
	v_lshl_add_u64 v[212:213], v[232:233], 0, s[62:63]
	s_addc_u32 s29, s69, 0
	s_add_i32 s30, s31, s11
	global_load_lds_dwordx4 v[212:213], off
	v_lshl_add_u64 v[212:213], s[28:29], 0, v[160:161]
	s_mov_b32 m0, s30
	s_nop 0
	global_load_lds_dwordx4 v[212:213], off
	v_lshl_add_u64 v[212:213], s[28:29], 0, v[164:165]
	s_add_i32 m0, s30, 0x2000
	s_nop 0
	global_load_lds_dwordx4 v[212:213], off
	v_lshl_add_u64 v[212:213], v[234:235], 0, s[62:63]
	s_mov_b32 m0, s18
	s_nop 0
	global_load_lds_dwordx4 v[212:213], off
	v_lshl_add_u64 v[212:213], v[236:237], 0, s[62:63]
	s_mov_b32 m0, s19
	s_nop 0
	global_load_lds_dwordx4 v[212:213], off
	s_waitcnt vmcnt(8)
	s_waitcnt lgkmcnt(0)
	s_barrier
	s_setprio 1
	s_waitcnt lgkmcnt(0)
	v_mfma_f32_16x16x32_bf16 v[62:65], v[130:133], v[176:179], v[62:65]
	v_mfma_f32_16x16x32_bf16 v[46:49], v[130:133], v[188:191], v[46:49]
	v_mfma_f32_16x16x32_bf16 v[30:33], v[130:133], v[196:199], v[30:33]
	v_mfma_f32_16x16x32_bf16 v[14:17], v[130:133], v[204:207], v[14:17]
	v_mfma_f32_16x16x32_bf16 v[62:65], v[134:137], v[180:183], v[62:65]
	v_mfma_f32_16x16x32_bf16 v[46:49], v[134:137], v[192:195], v[46:49]
	v_mfma_f32_16x16x32_bf16 v[30:33], v[134:137], v[200:203], v[30:33]
	v_mfma_f32_16x16x32_bf16 v[14:17], v[134:137], v[208:211], v[14:17]
	v_mfma_f32_16x16x32_bf16 v[58:61], v[138:141], v[176:179], v[58:61]
	v_mfma_f32_16x16x32_bf16 v[42:45], v[138:141], v[188:191], v[42:45]
	v_mfma_f32_16x16x32_bf16 v[26:29], v[138:141], v[196:199], v[26:29]
	v_mfma_f32_16x16x32_bf16 v[10:13], v[138:141], v[204:207], v[10:13]
	v_mfma_f32_16x16x32_bf16 v[58:61], v[142:145], v[180:183], v[58:61]
	v_mfma_f32_16x16x32_bf16 v[42:45], v[142:145], v[192:195], v[42:45]
	v_mfma_f32_16x16x32_bf16 v[26:29], v[142:145], v[200:203], v[26:29]
	v_mfma_f32_16x16x32_bf16 v[10:13], v[142:145], v[208:211], v[10:13]
	s_setprio 0
	s_setprio 1
	v_mfma_f32_16x16x32_bf16 v[54:57], v[146:149], v[176:179], v[54:57]
	v_mfma_f32_16x16x32_bf16 v[38:41], v[146:149], v[188:191], v[38:41]
	v_mfma_f32_16x16x32_bf16 v[22:25], v[146:149], v[196:199], v[22:25]
	v_mfma_f32_16x16x32_bf16 v[6:9], v[146:149], v[204:207], v[6:9]
	v_mfma_f32_16x16x32_bf16 v[54:57], v[150:153], v[180:183], v[54:57]
	v_mfma_f32_16x16x32_bf16 v[38:41], v[150:153], v[192:195], v[38:41]
	v_mfma_f32_16x16x32_bf16 v[22:25], v[150:153], v[200:203], v[22:25]
	v_mfma_f32_16x16x32_bf16 v[6:9], v[150:153], v[208:211], v[6:9]
	v_mfma_f32_16x16x32_bf16 v[50:53], v[154:157], v[176:179], v[50:53]
	v_mfma_f32_16x16x32_bf16 v[34:37], v[154:157], v[188:191], v[34:37]
	v_mfma_f32_16x16x32_bf16 v[18:21], v[154:157], v[196:199], v[18:21]
	v_mfma_f32_16x16x32_bf16 v[2:5], v[154:157], v[204:207], v[2:5]
	v_mfma_f32_16x16x32_bf16 v[50:53], v[172:175], v[180:183], v[50:53]
	v_mfma_f32_16x16x32_bf16 v[34:37], v[172:175], v[192:195], v[34:37]
	v_mfma_f32_16x16x32_bf16 v[18:21], v[172:175], v[200:203], v[18:21]
	v_mfma_f32_16x16x32_bf16 v[2:5], v[172:175], v[208:211], v[2:5]
	s_setprio 0
	s_barrier
	s_add_i32 s27, s27, 2
	s_add_u32 s54, s54, 0x100
	s_addc_u32 s55, s55, 0
	s_add_u32 s25, s25, 0x100
	s_addc_u32 s26, s26, 0
	s_cmp_gt_u32 s27, 29
	s_cbranch_scc0 .LBB0_32
	s_and_b64 vcc, exec, s[2:3]
	s_cbranch_vccz .LBB0_35
	s_barrier

.LBB0_132:
	s_add_u32 s23, s48, 0xfff80080
	s_addc_u32 s24, s49, -1
	s_add_i32 s25, 0, 0x10000
	s_cmp_eq_u32 s22, 28
	s_cselect_b32 s69, s3, s24
	s_cselect_b32 s68, s18, s23
	s_cselect_b32 s51, s1, s21
	s_cselect_b32 s50, s19, s20
	s_add_i32 s23, 0, 0x14000
	v_add_u32_e32 v156, s25, v165
	v_add_u32_e32 v169, s23, v165
	ds_read_b128 v[144:147], v156
	ds_read_b128 v[148:151], v156 offset:1024
	ds_read_b128 v[152:155], v156 offset:2048
	ds_read_b128 v[156:159], v156 offset:3072
	ds_read_b128 v[160:163], v169
	ds_read_b128 v[170:173], v169 offset:1024
	ds_read_b128 v[174:177], v169 offset:2048
	ds_read_b128 v[178:181], v169 offset:3072
	v_lshl_add_u64 v[232:233], s[48:49], 0, v[140:141]
	s_add_i32 m0, s45, 0xc000
	ds_read_b128 v[182:185], v168
	ds_read_b128 v[186:189], v168 offset:1024
	ds_read_b128 v[190:193], v168 offset:2048
	ds_read_b128 v[194:197], v168 offset:3072
	ds_read_b128 v[198:201], v168 offset:4096
	ds_read_b128 v[202:205], v168 offset:5120
	ds_read_b128 v[206:209], v168 offset:6144
	ds_read_b128 v[210:213], v168 offset:7168
	global_load_lds_dwordx4 v[232:233], off
	v_lshl_add_u64 v[232:233], s[48:49], 0, v[142:143]
	s_add_i32 m0, s45, 0xe000
	s_nop 0
	global_load_lds_dwordx4 v[232:233], off
	s_waitcnt vmcnt(8)
	s_waitcnt lgkmcnt(0)
	s_barrier
	s_setprio 1
	s_waitcnt lgkmcnt(0)
	v_mfma_f32_16x16x32_bf16 v[126:129], v[144:147], v[182:185], v[126:129]
	v_mfma_f32_16x16x32_bf16 v[110:113], v[144:147], v[190:193], v[110:113]
	v_mfma_f32_16x16x32_bf16 v[102:105], v[144:147], v[198:201], v[102:105]
	v_mfma_f32_16x16x32_bf16 v[86:89], v[144:147], v[206:209], v[86:89]
	v_mfma_f32_16x16x32_bf16 v[126:129], v[148:151], v[186:189], v[126:129]
	v_mfma_f32_16x16x32_bf16 v[110:113], v[148:151], v[194:197], v[110:113]
	v_mfma_f32_16x16x32_bf16 v[102:105], v[148:151], v[202:205], v[102:105]
	v_mfma_f32_16x16x32_bf16 v[86:89], v[148:151], v[210:213], v[86:89]
	v_mfma_f32_16x16x32_bf16 v[122:125], v[152:155], v[182:185], v[122:125]
	v_mfma_f32_16x16x32_bf16 v[106:109], v[152:155], v[190:193], v[106:109]
	v_mfma_f32_16x16x32_bf16 v[94:97], v[152:155], v[198:201], v[94:97]
	v_mfma_f32_16x16x32_bf16 v[78:81], v[152:155], v[206:209], v[78:81]
	v_mfma_f32_16x16x32_bf16 v[122:125], v[156:159], v[186:189], v[122:125]
	v_mfma_f32_16x16x32_bf16 v[106:109], v[156:159], v[194:197], v[106:109]
	v_mfma_f32_16x16x32_bf16 v[94:97], v[156:159], v[202:205], v[94:97]
	v_mfma_f32_16x16x32_bf16 v[78:81], v[156:159], v[210:213], v[78:81]
	s_setprio 0
	s_setprio 1
	v_mfma_f32_16x16x32_bf16 v[118:121], v[160:163], v[182:185], v[118:121]
	v_mfma_f32_16x16x32_bf16 v[98:101], v[160:163], v[190:193], v[98:101]
	v_mfma_f32_16x16x32_bf16 v[82:85], v[160:163], v[198:201], v[82:85]
	v_mfma_f32_16x16x32_bf16 v[70:73], v[160:163], v[206:209], v[70:73]
	v_mfma_f32_16x16x32_bf16 v[118:121], v[170:173], v[186:189], v[118:121]
	v_mfma_f32_16x16x32_bf16 v[98:101], v[170:173], v[194:197], v[98:101]
	v_mfma_f32_16x16x32_bf16 v[82:85], v[170:173], v[202:205], v[82:85]
	v_mfma_f32_16x16x32_bf16 v[70:73], v[170:173], v[210:213], v[70:73]
	v_mfma_f32_16x16x32_bf16 v[114:117], v[174:177], v[182:185], v[114:117]
	v_mfma_f32_16x16x32_bf16 v[90:93], v[174:177], v[190:193], v[90:93]
	v_mfma_f32_16x16x32_bf16 v[74:77], v[174:177], v[198:201], v[74:77]
	v_mfma_f32_16x16x32_bf16 v[66:69], v[174:177], v[206:209], v[66:69]
	v_mfma_f32_16x16x32_bf16 v[114:117], v[178:181], v[186:189], v[114:117]
	v_mfma_f32_16x16x32_bf16 v[90:93], v[178:181], v[194:197], v[90:93]
	v_mfma_f32_16x16x32_bf16 v[74:77], v[178:181], v[202:205], v[74:77]
	v_mfma_f32_16x16x32_bf16 v[66:69], v[178:181], v[210:213], v[66:69]
	s_setprio 0
	s_barrier
	s_add_i32 s24, s25, s16
	v_lshl_add_u64 v[232:233], s[50:51], 0, v[132:133]
	s_mov_b32 m0, s24
	ds_read_b128 v[182:185], v168 offset:16384
	ds_read_b128 v[186:189], v168 offset:17408
	ds_read_b128 v[190:193], v168 offset:18432
	ds_read_b128 v[194:197], v168 offset:19456
	ds_read_b128 v[198:201], v168 offset:20480
	ds_read_b128 v[202:205], v168 offset:21504
	ds_read_b128 v[206:209], v168 offset:22528
	ds_read_b128 v[210:213], v168 offset:23552
	global_load_lds_dwordx4 v[232:233], off
	s_add_i32 m0, s24, 0x2000
	s_add_u32 s24, s50, 0x80000
	v_lshl_add_u64 v[234:235], s[50:51], 0, v[136:137]
	s_addc_u32 s25, s51, 0
	s_add_i32 s23, s23, s16
	global_load_lds_dwordx4 v[234:235], off
	v_lshl_add_u64 v[236:237], s[24:25], 0, v[132:133]
	s_mov_b32 m0, s23
	v_lshl_add_u64 v[238:239], s[68:69], 0, v[134:135]
	global_load_lds_dwordx4 v[236:237], off
	v_lshl_add_u64 v[236:237], s[24:25], 0, v[136:137]
	s_add_i32 m0, s23, 0x2000
	s_nop 0
	global_load_lds_dwordx4 v[236:237], off
	v_lshl_add_u64 v[236:237], s[68:69], 0, v[130:131]
	s_mov_b32 m0, s45
	s_nop 0
	global_load_lds_dwordx4 v[236:237], off
	s_mov_b32 m0, s57
	s_nop 0
	global_load_lds_dwordx4 v[238:239], off
	s_waitcnt vmcnt(8)
	s_waitcnt lgkmcnt(0)
	s_barrier
	s_setprio 1
	s_waitcnt lgkmcnt(0)
	v_mfma_f32_16x16x32_bf16 v[62:65], v[144:147], v[182:185], v[62:65]
	v_mfma_f32_16x16x32_bf16 v[54:57], v[144:147], v[190:193], v[54:57]
	v_mfma_f32_16x16x32_bf16 v[38:41], v[144:147], v[198:201], v[38:41]
	v_mfma_f32_16x16x32_bf16 v[22:25], v[144:147], v[206:209], v[22:25]
	v_mfma_f32_16x16x32_bf16 v[62:65], v[148:151], v[186:189], v[62:65]
	v_mfma_f32_16x16x32_bf16 v[54:57], v[148:151], v[194:197], v[54:57]
	v_mfma_f32_16x16x32_bf16 v[38:41], v[148:151], v[202:205], v[38:41]
	v_mfma_f32_16x16x32_bf16 v[22:25], v[148:151], v[210:213], v[22:25]
	v_mfma_f32_16x16x32_bf16 v[58:61], v[152:155], v[182:185], v[58:61]
	v_mfma_f32_16x16x32_bf16 v[46:49], v[152:155], v[190:193], v[46:49]
	v_mfma_f32_16x16x32_bf16 v[30:33], v[152:155], v[198:201], v[30:33]
	v_mfma_f32_16x16x32_bf16 v[14:17], v[152:155], v[206:209], v[14:17]
	v_mfma_f32_16x16x32_bf16 v[58:61], v[156:159], v[186:189], v[58:61]
	v_mfma_f32_16x16x32_bf16 v[46:49], v[156:159], v[194:197], v[46:49]
	v_mfma_f32_16x16x32_bf16 v[30:33], v[156:159], v[202:205], v[30:33]
	v_mfma_f32_16x16x32_bf16 v[14:17], v[156:159], v[210:213], v[14:17]
	s_setprio 0
	s_setprio 1
	v_mfma_f32_16x16x32_bf16 v[50:53], v[160:163], v[182:185], v[50:53]
	v_mfma_f32_16x16x32_bf16 v[34:37], v[160:163], v[190:193], v[34:37]
	v_mfma_f32_16x16x32_bf16 v[18:21], v[160:163], v[198:201], v[18:21]
	v_mfma_f32_16x16x32_bf16 v[6:9], v[160:163], v[206:209], v[6:9]
	v_mfma_f32_16x16x32_bf16 v[50:53], v[170:173], v[186:189], v[50:53]
	v_mfma_f32_16x16x32_bf16 v[34:37], v[170:173], v[194:197], v[34:37]
	v_mfma_f32_16x16x32_bf16 v[18:21], v[170:173], v[202:205], v[18:21]
	v_mfma_f32_16x16x32_bf16 v[6:9], v[170:173], v[210:213], v[6:9]
	v_mfma_f32_16x16x32_bf16 v[42:45], v[174:177], v[182:185], v[42:45]
	v_mfma_f32_16x16x32_bf16 v[26:29], v[174:177], v[190:193], v[26:29]
	v_mfma_f32_16x16x32_bf16 v[10:13], v[174:177], v[198:201], v[10:13]
	v_mfma_f32_16x16x32_bf16 v[2:5], v[174:177], v[206:209], v[2:5]
	v_mfma_f32_16x16x32_bf16 v[42:45], v[178:181], v[186:189], v[42:45]
	v_mfma_f32_16x16x32_bf16 v[26:29], v[178:181], v[194:197], v[26:29]
	v_mfma_f32_16x16x32_bf16 v[10:13], v[178:181], v[202:205], v[10:13]
	v_mfma_f32_16x16x32_bf16 v[2:5], v[178:181], v[210:213], v[2:5]
	s_setprio 0
	s_barrier
	s_add_i32 s23, 0, 0x18000
	s_add_i32 s26, 0, 0x1c000
	v_add_u32_e32 v156, s23, v165
	v_add_u32_e32 v169, s26, v165
	ds_read_b128 v[144:147], v156
	ds_read_b128 v[148:151], v156 offset:1024
	ds_read_b128 v[152:155], v156 offset:2048
	ds_read_b128 v[156:159], v156 offset:3072
	ds_read_b128 v[160:163], v169
	ds_read_b128 v[170:173], v169 offset:1024
	ds_read_b128 v[174:177], v169 offset:2048
	ds_read_b128 v[178:181], v169 offset:3072
	s_add_u32 s24, s68, 0x80000
	s_addc_u32 s25, s69, 0
	s_mov_b32 m0, s42
	v_lshl_add_u64 v[240:241], s[24:25], 0, v[130:131]
	ds_read_b128 v[182:185], v168 offset:32768
	ds_read_b128 v[186:189], v168 offset:33792
	ds_read_b128 v[190:193], v168 offset:34816
	ds_read_b128 v[194:197], v168 offset:35840
	ds_read_b128 v[198:201], v168 offset:36864
	ds_read_b128 v[202:205], v168 offset:37888
	ds_read_b128 v[206:209], v168 offset:38912
	ds_read_b128 v[210:213], v168 offset:39936
	global_load_lds_dwordx4 v[240:241], off
	v_lshl_add_u64 v[240:241], s[24:25], 0, v[134:135]
	s_mov_b32 m0, s6
	s_nop 0
	global_load_lds_dwordx4 v[240:241], off
	s_waitcnt vmcnt(8)
	s_waitcnt lgkmcnt(0)
	s_barrier
	s_setprio 1
	s_waitcnt lgkmcnt(0)
	v_mfma_f32_16x16x32_bf16 v[126:129], v[144:147], v[182:185], v[126:129]
	v_mfma_f32_16x16x32_bf16 v[110:113], v[144:147], v[190:193], v[110:113]
	v_mfma_f32_16x16x32_bf16 v[102:105], v[144:147], v[198:201], v[102:105]
	v_mfma_f32_16x16x32_bf16 v[86:89], v[144:147], v[206:209], v[86:89]
	v_mfma_f32_16x16x32_bf16 v[126:129], v[148:151], v[186:189], v[126:129]
	v_mfma_f32_16x16x32_bf16 v[110:113], v[148:151], v[194:197], v[110:113]
	v_mfma_f32_16x16x32_bf16 v[102:105], v[148:151], v[202:205], v[102:105]
	v_mfma_f32_16x16x32_bf16 v[86:89], v[148:151], v[210:213], v[86:89]
	v_mfma_f32_16x16x32_bf16 v[122:125], v[152:155], v[182:185], v[122:125]
	v_mfma_f32_16x16x32_bf16 v[106:109], v[152:155], v[190:193], v[106:109]
	v_mfma_f32_16x16x32_bf16 v[94:97], v[152:155], v[198:201], v[94:97]
	v_mfma_f32_16x16x32_bf16 v[78:81], v[152:155], v[206:209], v[78:81]
	v_mfma_f32_16x16x32_bf16 v[122:125], v[156:159], v[186:189], v[122:125]
	v_mfma_f32_16x16x32_bf16 v[106:109], v[156:159], v[194:197], v[106:109]
	v_mfma_f32_16x16x32_bf16 v[94:97], v[156:159], v[202:205], v[94:97]
	v_mfma_f32_16x16x32_bf16 v[78:81], v[156:159], v[210:213], v[78:81]
	s_setprio 0
	s_setprio 1
	v_mfma_f32_16x16x32_bf16 v[118:121], v[160:163], v[182:185], v[118:121]
	v_mfma_f32_16x16x32_bf16 v[98:101], v[160:163], v[190:193], v[98:101]
	v_mfma_f32_16x16x32_bf16 v[82:85], v[160:163], v[198:201], v[82:85]
	v_mfma_f32_16x16x32_bf16 v[70:73], v[160:163], v[206:209], v[70:73]
	v_mfma_f32_16x16x32_bf16 v[118:121], v[170:173], v[186:189], v[118:121]
	v_mfma_f32_16x16x32_bf16 v[98:101], v[170:173], v[194:197], v[98:101]
	v_mfma_f32_16x16x32_bf16 v[82:85], v[170:173], v[202:205], v[82:85]
	v_mfma_f32_16x16x32_bf16 v[70:73], v[170:173], v[210:213], v[70:73]
	v_mfma_f32_16x16x32_bf16 v[114:117], v[174:177], v[182:185], v[114:117]
	v_mfma_f32_16x16x32_bf16 v[90:93], v[174:177], v[190:193], v[90:93]
	v_mfma_f32_16x16x32_bf16 v[74:77], v[174:177], v[198:201], v[74:77]
	v_mfma_f32_16x16x32_bf16 v[66:69], v[174:177], v[206:209], v[66:69]
	v_mfma_f32_16x16x32_bf16 v[114:117], v[178:181], v[186:189], v[114:117]
	v_mfma_f32_16x16x32_bf16 v[90:93], v[178:181], v[194:197], v[90:93]
	v_mfma_f32_16x16x32_bf16 v[74:77], v[178:181], v[202:205], v[74:77]
	v_mfma_f32_16x16x32_bf16 v[66:69], v[178:181], v[210:213], v[66:69]
	s_setprio 0
	s_barrier
	s_add_i32 s23, s23, s16
	v_lshl_add_u64 v[232:233], v[232:233], 0, s[62:63]
	s_mov_b32 m0, s23
	ds_read_b128 v[182:185], v168 offset:49152
	ds_read_b128 v[186:189], v168 offset:50176
	ds_read_b128 v[190:193], v168 offset:51200
	ds_read_b128 v[194:197], v168 offset:52224
	ds_read_b128 v[198:201], v168 offset:53248
	ds_read_b128 v[202:205], v168 offset:54272
	ds_read_b128 v[206:209], v168 offset:55296
	ds_read_b128 v[210:213], v168 offset:56320
	global_load_lds_dwordx4 v[232:233], off
	s_add_i32 m0, s23, 0x2000
	s_add_u32 s24, s50, 0x80080
	v_lshl_add_u64 v[232:233], v[234:235], 0, s[62:63]
	s_addc_u32 s25, s51, 0
	s_add_i32 s23, s26, s16
	global_load_lds_dwordx4 v[232:233], off
	v_lshl_add_u64 v[232:233], s[24:25], 0, v[132:133]
	s_mov_b32 m0, s23
	s_nop 0
	global_load_lds_dwordx4 v[232:233], off
	v_lshl_add_u64 v[232:233], s[24:25], 0, v[136:137]
	s_add_i32 m0, s23, 0x2000
	s_nop 0
	global_load_lds_dwordx4 v[232:233], off
	v_lshl_add_u64 v[232:233], v[236:237], 0, s[62:63]
	s_mov_b32 m0, s76
	s_nop 0
	global_load_lds_dwordx4 v[232:233], off
	v_lshl_add_u64 v[232:233], v[238:239], 0, s[62:63]
	s_mov_b32 m0, s77
	s_nop 0
	global_load_lds_dwordx4 v[232:233], off
	s_waitcnt vmcnt(8)
	s_waitcnt lgkmcnt(0)
	s_barrier
	s_setprio 1
	s_waitcnt lgkmcnt(0)
	v_mfma_f32_16x16x32_bf16 v[62:65], v[144:147], v[182:185], v[62:65]
	v_mfma_f32_16x16x32_bf16 v[54:57], v[144:147], v[190:193], v[54:57]
	v_mfma_f32_16x16x32_bf16 v[38:41], v[144:147], v[198:201], v[38:41]
	v_mfma_f32_16x16x32_bf16 v[22:25], v[144:147], v[206:209], v[22:25]
	v_mfma_f32_16x16x32_bf16 v[62:65], v[148:151], v[186:189], v[62:65]
	v_mfma_f32_16x16x32_bf16 v[54:57], v[148:151], v[194:197], v[54:57]
	v_mfma_f32_16x16x32_bf16 v[38:41], v[148:151], v[202:205], v[38:41]
	v_mfma_f32_16x16x32_bf16 v[22:25], v[148:151], v[210:213], v[22:25]
	v_mfma_f32_16x16x32_bf16 v[58:61], v[152:155], v[182:185], v[58:61]
	v_mfma_f32_16x16x32_bf16 v[46:49], v[152:155], v[190:193], v[46:49]
	v_mfma_f32_16x16x32_bf16 v[30:33], v[152:155], v[198:201], v[30:33]
	v_mfma_f32_16x16x32_bf16 v[14:17], v[152:155], v[206:209], v[14:17]
	v_mfma_f32_16x16x32_bf16 v[58:61], v[156:159], v[186:189], v[58:61]
	v_mfma_f32_16x16x32_bf16 v[46:49], v[156:159], v[194:197], v[46:49]
	v_mfma_f32_16x16x32_bf16 v[30:33], v[156:159], v[202:205], v[30:33]
	v_mfma_f32_16x16x32_bf16 v[14:17], v[156:159], v[210:213], v[14:17]
	s_setprio 0
	s_setprio 1
	v_mfma_f32_16x16x32_bf16 v[50:53], v[160:163], v[182:185], v[50:53]
	v_mfma_f32_16x16x32_bf16 v[34:37], v[160:163], v[190:193], v[34:37]
	v_mfma_f32_16x16x32_bf16 v[18:21], v[160:163], v[198:201], v[18:21]
	v_mfma_f32_16x16x32_bf16 v[6:9], v[160:163], v[206:209], v[6:9]
	v_mfma_f32_16x16x32_bf16 v[50:53], v[170:173], v[186:189], v[50:53]
	v_mfma_f32_16x16x32_bf16 v[34:37], v[170:173], v[194:197], v[34:37]
	v_mfma_f32_16x16x32_bf16 v[18:21], v[170:173], v[202:205], v[18:21]
	v_mfma_f32_16x16x32_bf16 v[6:9], v[170:173], v[210:213], v[6:9]
	v_mfma_f32_16x16x32_bf16 v[42:45], v[174:177], v[182:185], v[42:45]
	v_mfma_f32_16x16x32_bf16 v[26:29], v[174:177], v[190:193], v[26:29]
	v_mfma_f32_16x16x32_bf16 v[10:13], v[174:177], v[198:201], v[10:13]
	v_mfma_f32_16x16x32_bf16 v[2:5], v[174:177], v[206:209], v[2:5]
	v_mfma_f32_16x16x32_bf16 v[42:45], v[178:181], v[186:189], v[42:45]
	v_mfma_f32_16x16x32_bf16 v[26:29], v[178:181], v[194:197], v[26:29]
	v_mfma_f32_16x16x32_bf16 v[10:13], v[178:181], v[202:205], v[10:13]
	v_mfma_f32_16x16x32_bf16 v[2:5], v[178:181], v[210:213], v[2:5]
	s_setprio 0
	s_barrier
	s_add_i32 s22, s22, 2
	s_add_u32 s48, s48, 0x100
	s_addc_u32 s49, s49, 0
	s_add_u32 s20, s20, 0x100
	s_addc_u32 s21, s21, 0
	s_cmp_gt_u32 s22, 29
	s_cbranch_scc0 .LBB0_132
	s_and_b64 vcc, exec, s[10:11]
	s_cbranch_vccz .LBB0_135
	s_barrier

.LBB0_238:
	s_add_u32 s10, s12, 0x100
	s_addc_u32 s11, s13, 0
	s_add_i32 s23, 0, 0x10000
	s_cmpk_eq_i32 s22, 0x52
	s_cselect_b32 vcc_hi, s47, s11
	s_cselect_b32 vcc_lo, s46, s10
	s_cselect_b32 s51, s49, s21
	s_cselect_b32 s50, s48, s20
	s_add_i32 s24, 0, 0x14000
	v_add_u32_e32 v142, s23, v194
	v_add_u32_e32 v158, s24, v194
	ds_read_b128 v[122:125], v142
	ds_read_b128 v[126:129], v142 offset:1024
	ds_read_b128 v[138:141], v142 offset:2048
	ds_read_b128 v[142:145], v142 offset:3072
	ds_read_b128 v[146:149], v158
	ds_read_b128 v[150:153], v158 offset:1024
	ds_read_b128 v[154:157], v158 offset:2048
	ds_read_b128 v[158:161], v158 offset:3072
	v_lshl_add_u64 v[212:213], s[12:13], 0, v[170:171]
	s_add_i32 m0, s57, 0xc000
	ds_read_b128 v[174:177], v198
	ds_read_b128 v[178:181], v198 offset:1024
	ds_read_b128 v[182:185], v198 offset:2048
	ds_read_b128 v[186:189], v198 offset:3072
	ds_read_b128 v[190:193], v198 offset:4096
	ds_read_b128 v[200:203], v198 offset:5120
	ds_read_b128 v[204:207], v198 offset:6144
	ds_read_b128 v[208:211], v198 offset:7168
	global_load_lds_dwordx4 v[212:213], off
	v_lshl_add_u64 v[212:213], s[12:13], 0, v[172:173]
	s_add_i32 m0, s57, 0xe000
	s_nop 0
	global_load_lds_dwordx4 v[212:213], off
	s_waitcnt vmcnt(8)
	s_waitcnt lgkmcnt(0)
	s_barrier
	s_setprio 1
	s_waitcnt lgkmcnt(0)
	v_mfma_f32_16x16x32_bf16 v[134:137], v[122:125], v[174:177], v[134:137]
	v_mfma_f32_16x16x32_bf16 v[110:113], v[122:125], v[182:185], v[110:113]
	v_mfma_f32_16x16x32_bf16 v[94:97], v[122:125], v[190:193], v[94:97]
	v_mfma_f32_16x16x32_bf16 v[78:81], v[122:125], v[204:207], v[78:81]
	v_mfma_f32_16x16x32_bf16 v[134:137], v[126:129], v[178:181], v[134:137]
	v_mfma_f32_16x16x32_bf16 v[110:113], v[126:129], v[186:189], v[110:113]
	v_mfma_f32_16x16x32_bf16 v[94:97], v[126:129], v[200:203], v[94:97]
	v_mfma_f32_16x16x32_bf16 v[78:81], v[126:129], v[208:211], v[78:81]
	v_mfma_f32_16x16x32_bf16 v[130:133], v[138:141], v[174:177], v[130:133]
	v_mfma_f32_16x16x32_bf16 v[106:109], v[138:141], v[182:185], v[106:109]
	v_mfma_f32_16x16x32_bf16 v[90:93], v[138:141], v[190:193], v[90:93]
	v_mfma_f32_16x16x32_bf16 v[74:77], v[138:141], v[204:207], v[74:77]
	v_mfma_f32_16x16x32_bf16 v[130:133], v[142:145], v[178:181], v[130:133]
	v_mfma_f32_16x16x32_bf16 v[106:109], v[142:145], v[186:189], v[106:109]
	v_mfma_f32_16x16x32_bf16 v[90:93], v[142:145], v[200:203], v[90:93]
	v_mfma_f32_16x16x32_bf16 v[74:77], v[142:145], v[208:211], v[74:77]
	s_setprio 0
	s_setprio 1
	v_mfma_f32_16x16x32_bf16 v[118:121], v[146:149], v[174:177], v[118:121]
	v_mfma_f32_16x16x32_bf16 v[102:105], v[146:149], v[182:185], v[102:105]
	v_mfma_f32_16x16x32_bf16 v[86:89], v[146:149], v[190:193], v[86:89]
	v_mfma_f32_16x16x32_bf16 v[70:73], v[146:149], v[204:207], v[70:73]
	v_mfma_f32_16x16x32_bf16 v[118:121], v[150:153], v[178:181], v[118:121]
	v_mfma_f32_16x16x32_bf16 v[102:105], v[150:153], v[186:189], v[102:105]
	v_mfma_f32_16x16x32_bf16 v[86:89], v[150:153], v[200:203], v[86:89]
	v_mfma_f32_16x16x32_bf16 v[70:73], v[150:153], v[208:211], v[70:73]
	v_mfma_f32_16x16x32_bf16 v[114:117], v[154:157], v[174:177], v[114:117]
	v_mfma_f32_16x16x32_bf16 v[98:101], v[154:157], v[182:185], v[98:101]
	v_mfma_f32_16x16x32_bf16 v[82:85], v[154:157], v[190:193], v[82:85]
	v_mfma_f32_16x16x32_bf16 v[66:69], v[154:157], v[204:207], v[66:69]
	v_mfma_f32_16x16x32_bf16 v[114:117], v[158:161], v[178:181], v[114:117]
	v_mfma_f32_16x16x32_bf16 v[98:101], v[158:161], v[186:189], v[98:101]
	v_mfma_f32_16x16x32_bf16 v[82:85], v[158:161], v[200:203], v[82:85]
	v_mfma_f32_16x16x32_bf16 v[66:69], v[158:161], v[208:211], v[66:69]
	s_setprio 0
	s_barrier
	s_add_i32 s12, s23, s42
	v_lshl_add_u64 v[212:213], s[50:51], 0, v[164:165]
	s_mov_b32 m0, s12
	ds_read_b128 v[174:177], v198 offset:16384
	ds_read_b128 v[178:181], v198 offset:17408
	ds_read_b128 v[182:185], v198 offset:18432
	ds_read_b128 v[186:189], v198 offset:19456
	ds_read_b128 v[190:193], v198 offset:20480
	ds_read_b128 v[200:203], v198 offset:21504
	ds_read_b128 v[204:207], v198 offset:22528
	ds_read_b128 v[208:211], v198 offset:23552
	global_load_lds_dwordx4 v[212:213], off
	s_add_i32 m0, s12, 0x2000
	s_add_u32 s12, s50, 0x158000
	v_lshl_add_u64 v[232:233], s[50:51], 0, v[168:169]
	s_addc_u32 s13, s51, 0
	s_add_i32 s23, s24, s42
	global_load_lds_dwordx4 v[232:233], off
	v_lshl_add_u64 v[234:235], s[12:13], 0, v[164:165]
	s_mov_b32 m0, s23
	v_lshl_add_u64 v[236:237], vcc, 0, v[166:167]
	global_load_lds_dwordx4 v[234:235], off
	v_lshl_add_u64 v[234:235], s[12:13], 0, v[168:169]
	s_add_i32 m0, s23, 0x2000
	s_nop 0
	global_load_lds_dwordx4 v[234:235], off
	v_lshl_add_u64 v[234:235], vcc, 0, v[162:163]
	s_mov_b32 m0, s57
	s_nop 0
	global_load_lds_dwordx4 v[234:235], off
	s_mov_b32 m0, s58
	s_nop 0
	global_load_lds_dwordx4 v[236:237], off
	s_waitcnt vmcnt(8)
	s_waitcnt lgkmcnt(0)
	s_barrier
	s_setprio 1
	s_waitcnt lgkmcnt(0)
	v_mfma_f32_16x16x32_bf16 v[62:65], v[122:125], v[174:177], v[62:65]
	v_mfma_f32_16x16x32_bf16 v[46:49], v[122:125], v[182:185], v[46:49]
	v_mfma_f32_16x16x32_bf16 v[30:33], v[122:125], v[190:193], v[30:33]
	v_mfma_f32_16x16x32_bf16 v[14:17], v[122:125], v[204:207], v[14:17]
	v_mfma_f32_16x16x32_bf16 v[62:65], v[126:129], v[178:181], v[62:65]
	v_mfma_f32_16x16x32_bf16 v[46:49], v[126:129], v[186:189], v[46:49]
	v_mfma_f32_16x16x32_bf16 v[30:33], v[126:129], v[200:203], v[30:33]
	v_mfma_f32_16x16x32_bf16 v[14:17], v[126:129], v[208:211], v[14:17]
	v_mfma_f32_16x16x32_bf16 v[58:61], v[138:141], v[174:177], v[58:61]
	v_mfma_f32_16x16x32_bf16 v[42:45], v[138:141], v[182:185], v[42:45]
	v_mfma_f32_16x16x32_bf16 v[26:29], v[138:141], v[190:193], v[26:29]
	v_mfma_f32_16x16x32_bf16 v[10:13], v[138:141], v[204:207], v[10:13]
	v_mfma_f32_16x16x32_bf16 v[58:61], v[142:145], v[178:181], v[58:61]
	v_mfma_f32_16x16x32_bf16 v[42:45], v[142:145], v[186:189], v[42:45]
	v_mfma_f32_16x16x32_bf16 v[26:29], v[142:145], v[200:203], v[26:29]
	v_mfma_f32_16x16x32_bf16 v[10:13], v[142:145], v[208:211], v[10:13]
	s_setprio 0
	s_setprio 1
	v_mfma_f32_16x16x32_bf16 v[54:57], v[146:149], v[174:177], v[54:57]
	v_mfma_f32_16x16x32_bf16 v[38:41], v[146:149], v[182:185], v[38:41]
	v_mfma_f32_16x16x32_bf16 v[22:25], v[146:149], v[190:193], v[22:25]
	v_mfma_f32_16x16x32_bf16 v[6:9], v[146:149], v[204:207], v[6:9]
	v_mfma_f32_16x16x32_bf16 v[54:57], v[150:153], v[178:181], v[54:57]
	v_mfma_f32_16x16x32_bf16 v[38:41], v[150:153], v[186:189], v[38:41]
	v_mfma_f32_16x16x32_bf16 v[22:25], v[150:153], v[200:203], v[22:25]
	v_mfma_f32_16x16x32_bf16 v[6:9], v[150:153], v[208:211], v[6:9]
	v_mfma_f32_16x16x32_bf16 v[50:53], v[154:157], v[174:177], v[50:53]
	v_mfma_f32_16x16x32_bf16 v[34:37], v[154:157], v[182:185], v[34:37]
	v_mfma_f32_16x16x32_bf16 v[18:21], v[154:157], v[190:193], v[18:21]
	v_mfma_f32_16x16x32_bf16 v[2:5], v[154:157], v[204:207], v[2:5]
	v_mfma_f32_16x16x32_bf16 v[50:53], v[158:161], v[178:181], v[50:53]
	v_mfma_f32_16x16x32_bf16 v[34:37], v[158:161], v[186:189], v[34:37]
	v_mfma_f32_16x16x32_bf16 v[18:21], v[158:161], v[200:203], v[18:21]
	v_mfma_f32_16x16x32_bf16 v[2:5], v[158:161], v[208:211], v[2:5]
	s_setprio 0
	s_barrier
	s_add_i32 s23, 0, 0x18000
	s_add_i32 s24, 0, 0x1c000
	v_add_u32_e32 v142, s23, v194
	v_add_u32_e32 v158, s24, v194
	ds_read_b128 v[122:125], v142
	ds_read_b128 v[126:129], v142 offset:1024
	ds_read_b128 v[138:141], v142 offset:2048
	ds_read_b128 v[142:145], v142 offset:3072
	ds_read_b128 v[146:149], v158
	ds_read_b128 v[150:153], v158 offset:1024
	ds_read_b128 v[154:157], v158 offset:2048
	ds_read_b128 v[158:161], v158 offset:3072
	s_add_u32 s12, vcc_lo, 0x158000
	s_addc_u32 s13, vcc_hi, 0
	s_mov_b32 m0, s67
	v_lshl_add_u64 v[238:239], s[12:13], 0, v[162:163]
	ds_read_b128 v[174:177], v198 offset:32768
	ds_read_b128 v[178:181], v198 offset:33792
	ds_read_b128 v[182:185], v198 offset:34816
	ds_read_b128 v[186:189], v198 offset:35840
	ds_read_b128 v[190:193], v198 offset:36864
	ds_read_b128 v[200:203], v198 offset:37888
	ds_read_b128 v[204:207], v198 offset:38912
	ds_read_b128 v[208:211], v198 offset:39936
	global_load_lds_dwordx4 v[238:239], off
	v_lshl_add_u64 v[238:239], s[12:13], 0, v[166:167]
	s_mov_b32 m0, s76
	s_nop 0
	global_load_lds_dwordx4 v[238:239], off
	s_waitcnt vmcnt(8)
	s_waitcnt lgkmcnt(0)
	s_barrier
	s_setprio 1
	s_waitcnt lgkmcnt(0)
	v_mfma_f32_16x16x32_bf16 v[134:137], v[122:125], v[174:177], v[134:137]
	v_mfma_f32_16x16x32_bf16 v[110:113], v[122:125], v[182:185], v[110:113]
	v_mfma_f32_16x16x32_bf16 v[94:97], v[122:125], v[190:193], v[94:97]
	v_mfma_f32_16x16x32_bf16 v[78:81], v[122:125], v[204:207], v[78:81]
	v_mfma_f32_16x16x32_bf16 v[134:137], v[126:129], v[178:181], v[134:137]
	v_mfma_f32_16x16x32_bf16 v[110:113], v[126:129], v[186:189], v[110:113]
	v_mfma_f32_16x16x32_bf16 v[94:97], v[126:129], v[200:203], v[94:97]
	v_mfma_f32_16x16x32_bf16 v[78:81], v[126:129], v[208:211], v[78:81]
	v_mfma_f32_16x16x32_bf16 v[130:133], v[138:141], v[174:177], v[130:133]
	v_mfma_f32_16x16x32_bf16 v[106:109], v[138:141], v[182:185], v[106:109]
	v_mfma_f32_16x16x32_bf16 v[90:93], v[138:141], v[190:193], v[90:93]
	v_mfma_f32_16x16x32_bf16 v[74:77], v[138:141], v[204:207], v[74:77]
	v_mfma_f32_16x16x32_bf16 v[130:133], v[142:145], v[178:181], v[130:133]
	v_mfma_f32_16x16x32_bf16 v[106:109], v[142:145], v[186:189], v[106:109]
	v_mfma_f32_16x16x32_bf16 v[90:93], v[142:145], v[200:203], v[90:93]
	v_mfma_f32_16x16x32_bf16 v[74:77], v[142:145], v[208:211], v[74:77]
	s_setprio 0
	s_setprio 1
	v_mfma_f32_16x16x32_bf16 v[118:121], v[146:149], v[174:177], v[118:121]
	v_mfma_f32_16x16x32_bf16 v[102:105], v[146:149], v[182:185], v[102:105]
	v_mfma_f32_16x16x32_bf16 v[86:89], v[146:149], v[190:193], v[86:89]
	v_mfma_f32_16x16x32_bf16 v[70:73], v[146:149], v[204:207], v[70:73]
	v_mfma_f32_16x16x32_bf16 v[118:121], v[150:153], v[178:181], v[118:121]
	v_mfma_f32_16x16x32_bf16 v[102:105], v[150:153], v[186:189], v[102:105]
	v_mfma_f32_16x16x32_bf16 v[86:89], v[150:153], v[200:203], v[86:89]
	v_mfma_f32_16x16x32_bf16 v[70:73], v[150:153], v[208:211], v[70:73]
	v_mfma_f32_16x16x32_bf16 v[114:117], v[154:157], v[174:177], v[114:117]
	v_mfma_f32_16x16x32_bf16 v[98:101], v[154:157], v[182:185], v[98:101]
	v_mfma_f32_16x16x32_bf16 v[82:85], v[154:157], v[190:193], v[82:85]
	v_mfma_f32_16x16x32_bf16 v[66:69], v[154:157], v[204:207], v[66:69]
	v_mfma_f32_16x16x32_bf16 v[114:117], v[158:161], v[178:181], v[114:117]
	v_mfma_f32_16x16x32_bf16 v[98:101], v[158:161], v[186:189], v[98:101]
	v_mfma_f32_16x16x32_bf16 v[82:85], v[158:161], v[200:203], v[82:85]
	v_mfma_f32_16x16x32_bf16 v[66:69], v[158:161], v[208:211], v[66:69]
	s_setprio 0
	s_barrier
	s_add_i32 s12, s23, s42
	v_lshl_add_u64 v[212:213], v[212:213], 0, s[62:63]
	s_mov_b32 m0, s12
	ds_read_b128 v[174:177], v198 offset:49152
	ds_read_b128 v[178:181], v198 offset:50176
	ds_read_b128 v[182:185], v198 offset:51200
	ds_read_b128 v[186:189], v198 offset:52224
	ds_read_b128 v[190:193], v198 offset:53248
	ds_read_b128 v[200:203], v198 offset:54272
	ds_read_b128 v[204:207], v198 offset:55296
	ds_read_b128 v[208:211], v198 offset:56320
	global_load_lds_dwordx4 v[212:213], off
	s_add_i32 m0, s12, 0x2000
	s_add_u32 s12, s50, 0x158080
	v_lshl_add_u64 v[212:213], v[232:233], 0, s[62:63]
	s_addc_u32 s13, s51, 0
	s_add_i32 s23, s24, s42
	global_load_lds_dwordx4 v[212:213], off
	v_lshl_add_u64 v[212:213], s[12:13], 0, v[164:165]
	s_mov_b32 m0, s23
	s_nop 0
	global_load_lds_dwordx4 v[212:213], off
	v_lshl_add_u64 v[212:213], s[12:13], 0, v[168:169]
	s_add_i32 m0, s23, 0x2000
	s_nop 0
	global_load_lds_dwordx4 v[212:213], off
	v_lshl_add_u64 v[212:213], v[234:235], 0, s[62:63]
	s_mov_b32 m0, s1
	s_nop 0
	global_load_lds_dwordx4 v[212:213], off
	v_lshl_add_u64 v[212:213], v[236:237], 0, s[62:63]
	s_mov_b32 m0, s52
	s_nop 0
	global_load_lds_dwordx4 v[212:213], off
	s_waitcnt vmcnt(8)
	s_waitcnt lgkmcnt(0)
	s_barrier
	s_setprio 1
	s_waitcnt lgkmcnt(0)
	v_mfma_f32_16x16x32_bf16 v[62:65], v[122:125], v[174:177], v[62:65]
	v_mfma_f32_16x16x32_bf16 v[46:49], v[122:125], v[182:185], v[46:49]
	v_mfma_f32_16x16x32_bf16 v[30:33], v[122:125], v[190:193], v[30:33]
	v_mfma_f32_16x16x32_bf16 v[14:17], v[122:125], v[204:207], v[14:17]
	v_mfma_f32_16x16x32_bf16 v[62:65], v[126:129], v[178:181], v[62:65]
	v_mfma_f32_16x16x32_bf16 v[46:49], v[126:129], v[186:189], v[46:49]
	v_mfma_f32_16x16x32_bf16 v[30:33], v[126:129], v[200:203], v[30:33]
	v_mfma_f32_16x16x32_bf16 v[14:17], v[126:129], v[208:211], v[14:17]
	v_mfma_f32_16x16x32_bf16 v[58:61], v[138:141], v[174:177], v[58:61]
	v_mfma_f32_16x16x32_bf16 v[42:45], v[138:141], v[182:185], v[42:45]
	v_mfma_f32_16x16x32_bf16 v[26:29], v[138:141], v[190:193], v[26:29]
	v_mfma_f32_16x16x32_bf16 v[10:13], v[138:141], v[204:207], v[10:13]
	v_mfma_f32_16x16x32_bf16 v[58:61], v[142:145], v[178:181], v[58:61]
	v_mfma_f32_16x16x32_bf16 v[42:45], v[142:145], v[186:189], v[42:45]
	v_mfma_f32_16x16x32_bf16 v[26:29], v[142:145], v[200:203], v[26:29]
	v_mfma_f32_16x16x32_bf16 v[10:13], v[142:145], v[208:211], v[10:13]
	s_setprio 0
	s_setprio 1
	v_mfma_f32_16x16x32_bf16 v[54:57], v[146:149], v[174:177], v[54:57]
	v_mfma_f32_16x16x32_bf16 v[38:41], v[146:149], v[182:185], v[38:41]
	v_mfma_f32_16x16x32_bf16 v[22:25], v[146:149], v[190:193], v[22:25]
	v_mfma_f32_16x16x32_bf16 v[6:9], v[146:149], v[204:207], v[6:9]
	v_mfma_f32_16x16x32_bf16 v[54:57], v[150:153], v[178:181], v[54:57]
	v_mfma_f32_16x16x32_bf16 v[38:41], v[150:153], v[186:189], v[38:41]
	v_mfma_f32_16x16x32_bf16 v[22:25], v[150:153], v[200:203], v[22:25]
	v_mfma_f32_16x16x32_bf16 v[6:9], v[150:153], v[208:211], v[6:9]
	v_mfma_f32_16x16x32_bf16 v[50:53], v[154:157], v[174:177], v[50:53]
	v_mfma_f32_16x16x32_bf16 v[34:37], v[154:157], v[182:185], v[34:37]
	v_mfma_f32_16x16x32_bf16 v[18:21], v[154:157], v[190:193], v[18:21]
	v_mfma_f32_16x16x32_bf16 v[2:5], v[154:157], v[204:207], v[2:5]
	v_mfma_f32_16x16x32_bf16 v[50:53], v[158:161], v[178:181], v[50:53]
	v_mfma_f32_16x16x32_bf16 v[34:37], v[158:161], v[186:189], v[34:37]
	v_mfma_f32_16x16x32_bf16 v[18:21], v[158:161], v[200:203], v[18:21]
	v_mfma_f32_16x16x32_bf16 v[2:5], v[158:161], v[208:211], v[2:5]
	s_setprio 0
	s_barrier
	s_add_i32 s22, s22, 2
	s_add_u32 s20, s20, 0x100
	s_addc_u32 s21, s21, 0
	s_cmpk_gt_u32 s22, 0x53
	s_mov_b64 s[12:13], s[10:11]
	s_cbranch_scc0 .LBB0_238
	s_and_b64 vcc, exec, s[2:3]
	s_cbranch_vccz .LBB0_241
	s_barrier

.LBB0_340:
	s_add_u32 s22, s46, 0xfff80080
	s_addc_u32 s23, s47, -1
	s_add_i32 s24, 0, 0x10000
	s_cmp_eq_u32 s21, 28
	s_cselect_b32 s51, s1, s23
	s_cselect_b32 s50, s13, s22
	v_add_u32_e32 v148, s24, v152
	s_cselect_b32 s49, s11, s20
	s_cselect_b32 s48, s18, s19
	s_add_i32 s25, 0, 0x14000
	ds_read_b128 v[144:147], v148
	ds_read_b128 v[156:159], v148 offset:1024
	ds_read_b128 v[160:163], v148 offset:2048
	ds_read_b128 v[164:167], v148 offset:3072
	v_add_u32_e32 v148, s25, v152
	ds_read_b128 v[168:171], v148
	ds_read_b128 v[172:175], v148 offset:1024
	ds_read_b128 v[176:179], v148 offset:2048
	ds_read_b128 v[180:183], v148 offset:3072
	v_lshl_add_u64 v[148:149], s[46:47], 0, v[140:141]
	s_add_i32 m0, s3, 0xc000
	ds_read_b128 v[184:187], v154
	ds_read_b128 v[188:191], v154 offset:1024
	ds_read_b128 v[192:195], v154 offset:2048
	ds_read_b128 v[196:199], v154 offset:3072
	ds_read_b128 v[200:203], v154 offset:4096
	ds_read_b128 v[204:207], v154 offset:5120
	ds_read_b128 v[208:211], v154 offset:6144
	ds_read_b128 v[232:235], v154 offset:7168
	global_load_lds_dwordx4 v[148:149], off
	v_lshl_add_u64 v[148:149], s[46:47], 0, v[142:143]
	s_add_i32 m0, s3, 0xe000
	s_nop 0
	global_load_lds_dwordx4 v[148:149], off
	s_waitcnt vmcnt(8)
	s_waitcnt lgkmcnt(0)
	s_barrier
	s_setprio 1
	s_waitcnt lgkmcnt(0)
	v_mfma_f32_16x16x32_bf16 v[126:129], v[144:147], v[184:187], v[126:129]
	v_mfma_f32_16x16x32_bf16 v[110:113], v[144:147], v[192:195], v[110:113]
	v_mfma_f32_16x16x32_bf16 v[94:97], v[144:147], v[200:203], v[94:97]
	v_mfma_f32_16x16x32_bf16 v[78:81], v[144:147], v[208:211], v[78:81]
	v_mfma_f32_16x16x32_bf16 v[126:129], v[156:159], v[188:191], v[126:129]
	v_mfma_f32_16x16x32_bf16 v[110:113], v[156:159], v[196:199], v[110:113]
	v_mfma_f32_16x16x32_bf16 v[94:97], v[156:159], v[204:207], v[94:97]
	v_mfma_f32_16x16x32_bf16 v[78:81], v[156:159], v[232:235], v[78:81]
	v_mfma_f32_16x16x32_bf16 v[122:125], v[160:163], v[184:187], v[122:125]
	v_mfma_f32_16x16x32_bf16 v[106:109], v[160:163], v[192:195], v[106:109]
	v_mfma_f32_16x16x32_bf16 v[90:93], v[160:163], v[200:203], v[90:93]
	v_mfma_f32_16x16x32_bf16 v[74:77], v[160:163], v[208:211], v[74:77]
	v_mfma_f32_16x16x32_bf16 v[122:125], v[164:167], v[188:191], v[122:125]
	v_mfma_f32_16x16x32_bf16 v[106:109], v[164:167], v[196:199], v[106:109]
	v_mfma_f32_16x16x32_bf16 v[90:93], v[164:167], v[204:207], v[90:93]
	v_mfma_f32_16x16x32_bf16 v[74:77], v[164:167], v[232:235], v[74:77]
	s_setprio 0
	s_setprio 1
	v_mfma_f32_16x16x32_bf16 v[118:121], v[168:171], v[184:187], v[118:121]
	v_mfma_f32_16x16x32_bf16 v[102:105], v[168:171], v[192:195], v[102:105]
	v_mfma_f32_16x16x32_bf16 v[86:89], v[168:171], v[200:203], v[86:89]
	v_mfma_f32_16x16x32_bf16 v[70:73], v[168:171], v[208:211], v[70:73]
	v_mfma_f32_16x16x32_bf16 v[118:121], v[172:175], v[188:191], v[118:121]
	v_mfma_f32_16x16x32_bf16 v[102:105], v[172:175], v[196:199], v[102:105]
	v_mfma_f32_16x16x32_bf16 v[86:89], v[172:175], v[204:207], v[86:89]
	v_mfma_f32_16x16x32_bf16 v[70:73], v[172:175], v[232:235], v[70:73]
	v_mfma_f32_16x16x32_bf16 v[114:117], v[176:179], v[184:187], v[114:117]
	v_mfma_f32_16x16x32_bf16 v[98:101], v[176:179], v[192:195], v[98:101]
	v_mfma_f32_16x16x32_bf16 v[82:85], v[176:179], v[200:203], v[82:85]
	v_mfma_f32_16x16x32_bf16 v[66:69], v[176:179], v[208:211], v[66:69]
	v_mfma_f32_16x16x32_bf16 v[114:117], v[180:183], v[188:191], v[114:117]
	v_mfma_f32_16x16x32_bf16 v[98:101], v[180:183], v[196:199], v[98:101]
	v_mfma_f32_16x16x32_bf16 v[82:85], v[180:183], v[204:207], v[82:85]
	v_mfma_f32_16x16x32_bf16 v[66:69], v[180:183], v[232:235], v[66:69]
	s_setprio 0
	s_barrier
	s_add_i32 s22, s24, s16
	v_lshl_add_u64 v[148:149], s[48:49], 0, v[134:135]
	s_mov_b32 m0, s22
	ds_read_b128 v[184:187], v154 offset:16384
	ds_read_b128 v[188:191], v154 offset:17408
	ds_read_b128 v[192:195], v154 offset:18432
	ds_read_b128 v[196:199], v154 offset:19456
	ds_read_b128 v[200:203], v154 offset:20480
	ds_read_b128 v[204:207], v154 offset:21504
	ds_read_b128 v[208:211], v154 offset:22528
	ds_read_b128 v[232:235], v154 offset:23552
	global_load_lds_dwordx4 v[148:149], off
	s_add_i32 m0, s22, 0x2000
	s_add_u32 s22, s48, 0x80000
	v_lshl_add_u64 v[212:213], s[48:49], 0, v[130:131]
	s_addc_u32 s23, s49, 0
	s_add_i32 s24, s25, s16
	global_load_lds_dwordx4 v[212:213], off
	v_lshl_add_u64 v[236:237], s[22:23], 0, v[134:135]
	s_mov_b32 m0, s24
	v_lshl_add_u64 v[238:239], s[50:51], 0, v[132:133]
	global_load_lds_dwordx4 v[236:237], off
	v_lshl_add_u64 v[236:237], s[22:23], 0, v[130:131]
	s_add_i32 m0, s24, 0x2000
	s_nop 0
	global_load_lds_dwordx4 v[236:237], off
	v_lshl_add_u64 v[236:237], s[50:51], 0, v[136:137]
	s_mov_b32 m0, s3
	s_nop 0
	global_load_lds_dwordx4 v[236:237], off
	s_mov_b32 m0, s55
	s_nop 0
	global_load_lds_dwordx4 v[238:239], off
	s_waitcnt vmcnt(8)
	s_waitcnt lgkmcnt(0)
	s_barrier
	s_setprio 1
	s_waitcnt lgkmcnt(0)
	v_mfma_f32_16x16x32_bf16 v[62:65], v[144:147], v[184:187], v[62:65]
	v_mfma_f32_16x16x32_bf16 v[46:49], v[144:147], v[192:195], v[46:49]
	v_mfma_f32_16x16x32_bf16 v[30:33], v[144:147], v[200:203], v[30:33]
	v_mfma_f32_16x16x32_bf16 v[14:17], v[144:147], v[208:211], v[14:17]
	v_mfma_f32_16x16x32_bf16 v[62:65], v[156:159], v[188:191], v[62:65]
	v_mfma_f32_16x16x32_bf16 v[46:49], v[156:159], v[196:199], v[46:49]
	v_mfma_f32_16x16x32_bf16 v[30:33], v[156:159], v[204:207], v[30:33]
	v_mfma_f32_16x16x32_bf16 v[14:17], v[156:159], v[232:235], v[14:17]
	v_mfma_f32_16x16x32_bf16 v[58:61], v[160:163], v[184:187], v[58:61]
	v_mfma_f32_16x16x32_bf16 v[42:45], v[160:163], v[192:195], v[42:45]
	v_mfma_f32_16x16x32_bf16 v[26:29], v[160:163], v[200:203], v[26:29]
	v_mfma_f32_16x16x32_bf16 v[10:13], v[160:163], v[208:211], v[10:13]
	v_mfma_f32_16x16x32_bf16 v[58:61], v[164:167], v[188:191], v[58:61]
	v_mfma_f32_16x16x32_bf16 v[42:45], v[164:167], v[196:199], v[42:45]
	v_mfma_f32_16x16x32_bf16 v[26:29], v[164:167], v[204:207], v[26:29]
	v_mfma_f32_16x16x32_bf16 v[10:13], v[164:167], v[232:235], v[10:13]
	s_setprio 0
	s_setprio 1
	v_mfma_f32_16x16x32_bf16 v[54:57], v[168:171], v[184:187], v[54:57]
	v_mfma_f32_16x16x32_bf16 v[38:41], v[168:171], v[192:195], v[38:41]
	v_mfma_f32_16x16x32_bf16 v[22:25], v[168:171], v[200:203], v[22:25]
	v_mfma_f32_16x16x32_bf16 v[6:9], v[168:171], v[208:211], v[6:9]
	v_mfma_f32_16x16x32_bf16 v[54:57], v[172:175], v[188:191], v[54:57]
	v_mfma_f32_16x16x32_bf16 v[38:41], v[172:175], v[196:199], v[38:41]
	v_mfma_f32_16x16x32_bf16 v[22:25], v[172:175], v[204:207], v[22:25]
	v_mfma_f32_16x16x32_bf16 v[6:9], v[172:175], v[232:235], v[6:9]
	v_mfma_f32_16x16x32_bf16 v[50:53], v[176:179], v[184:187], v[50:53]
	v_mfma_f32_16x16x32_bf16 v[34:37], v[176:179], v[192:195], v[34:37]
	v_mfma_f32_16x16x32_bf16 v[18:21], v[176:179], v[200:203], v[18:21]
	v_mfma_f32_16x16x32_bf16 v[2:5], v[176:179], v[208:211], v[2:5]
	v_mfma_f32_16x16x32_bf16 v[50:53], v[180:183], v[188:191], v[50:53]
	v_mfma_f32_16x16x32_bf16 v[34:37], v[180:183], v[196:199], v[34:37]
	v_mfma_f32_16x16x32_bf16 v[18:21], v[180:183], v[204:207], v[18:21]
	v_mfma_f32_16x16x32_bf16 v[2:5], v[180:183], v[232:235], v[2:5]
	s_setprio 0
	s_barrier
	s_add_i32 s24, 0, 0x18000
	v_add_u32_e32 v155, s24, v152
	s_add_i32 s25, 0, 0x1c000
	ds_read_b128 v[144:147], v155
	ds_read_b128 v[156:159], v155 offset:1024
	ds_read_b128 v[160:163], v155 offset:2048
	ds_read_b128 v[164:167], v155 offset:3072
	v_add_u32_e32 v155, s25, v152
	ds_read_b128 v[168:171], v155
	ds_read_b128 v[172:175], v155 offset:1024
	ds_read_b128 v[176:179], v155 offset:2048
	ds_read_b128 v[180:183], v155 offset:3072
	s_add_u32 s22, s50, 0x80000
	s_addc_u32 s23, s51, 0
	s_mov_b32 m0, s57
	v_lshl_add_u64 v[240:241], s[22:23], 0, v[136:137]
	ds_read_b128 v[184:187], v154 offset:32768
	ds_read_b128 v[188:191], v154 offset:33792
	ds_read_b128 v[192:195], v154 offset:34816
	ds_read_b128 v[196:199], v154 offset:35840
	ds_read_b128 v[200:203], v154 offset:36864
	ds_read_b128 v[204:207], v154 offset:37888
	ds_read_b128 v[208:211], v154 offset:38912
	ds_read_b128 v[232:235], v154 offset:39936
	global_load_lds_dwordx4 v[240:241], off
	v_lshl_add_u64 v[240:241], s[22:23], 0, v[132:133]
	s_mov_b32 m0, s68
	s_nop 0
	global_load_lds_dwordx4 v[240:241], off
	s_waitcnt vmcnt(8)
	s_waitcnt lgkmcnt(0)
	s_barrier
	s_setprio 1
	s_waitcnt lgkmcnt(0)
	v_mfma_f32_16x16x32_bf16 v[126:129], v[144:147], v[184:187], v[126:129]
	v_mfma_f32_16x16x32_bf16 v[110:113], v[144:147], v[192:195], v[110:113]
	v_mfma_f32_16x16x32_bf16 v[94:97], v[144:147], v[200:203], v[94:97]
	v_mfma_f32_16x16x32_bf16 v[78:81], v[144:147], v[208:211], v[78:81]
	v_mfma_f32_16x16x32_bf16 v[126:129], v[156:159], v[188:191], v[126:129]
	v_mfma_f32_16x16x32_bf16 v[110:113], v[156:159], v[196:199], v[110:113]
	v_mfma_f32_16x16x32_bf16 v[94:97], v[156:159], v[204:207], v[94:97]
	v_mfma_f32_16x16x32_bf16 v[78:81], v[156:159], v[232:235], v[78:81]
	v_mfma_f32_16x16x32_bf16 v[122:125], v[160:163], v[184:187], v[122:125]
	v_mfma_f32_16x16x32_bf16 v[106:109], v[160:163], v[192:195], v[106:109]
	v_mfma_f32_16x16x32_bf16 v[90:93], v[160:163], v[200:203], v[90:93]
	v_mfma_f32_16x16x32_bf16 v[74:77], v[160:163], v[208:211], v[74:77]
	v_mfma_f32_16x16x32_bf16 v[122:125], v[164:167], v[188:191], v[122:125]
	v_mfma_f32_16x16x32_bf16 v[106:109], v[164:167], v[196:199], v[106:109]
	v_mfma_f32_16x16x32_bf16 v[90:93], v[164:167], v[204:207], v[90:93]
	v_mfma_f32_16x16x32_bf16 v[74:77], v[164:167], v[232:235], v[74:77]
	s_setprio 0
	s_setprio 1
	v_mfma_f32_16x16x32_bf16 v[118:121], v[168:171], v[184:187], v[118:121]
	v_mfma_f32_16x16x32_bf16 v[102:105], v[168:171], v[192:195], v[102:105]
	v_mfma_f32_16x16x32_bf16 v[86:89], v[168:171], v[200:203], v[86:89]
	v_mfma_f32_16x16x32_bf16 v[70:73], v[168:171], v[208:211], v[70:73]
	v_mfma_f32_16x16x32_bf16 v[118:121], v[172:175], v[188:191], v[118:121]
	v_mfma_f32_16x16x32_bf16 v[102:105], v[172:175], v[196:199], v[102:105]
	v_mfma_f32_16x16x32_bf16 v[86:89], v[172:175], v[204:207], v[86:89]
	v_mfma_f32_16x16x32_bf16 v[70:73], v[172:175], v[232:235], v[70:73]
	v_mfma_f32_16x16x32_bf16 v[114:117], v[176:179], v[184:187], v[114:117]
	v_mfma_f32_16x16x32_bf16 v[98:101], v[176:179], v[192:195], v[98:101]
	v_mfma_f32_16x16x32_bf16 v[82:85], v[176:179], v[200:203], v[82:85]
	v_mfma_f32_16x16x32_bf16 v[66:69], v[176:179], v[208:211], v[66:69]
	v_mfma_f32_16x16x32_bf16 v[114:117], v[180:183], v[188:191], v[114:117]
	v_mfma_f32_16x16x32_bf16 v[98:101], v[180:183], v[196:199], v[98:101]
	v_mfma_f32_16x16x32_bf16 v[82:85], v[180:183], v[204:207], v[82:85]
	v_mfma_f32_16x16x32_bf16 v[66:69], v[180:183], v[232:235], v[66:69]
	s_setprio 0
	s_barrier
	s_add_i32 s22, s24, s16
	v_lshl_add_u64 v[148:149], v[148:149], 0, s[62:63]
	s_mov_b32 m0, s22
	ds_read_b128 v[184:187], v154 offset:49152
	ds_read_b128 v[188:191], v154 offset:50176
	ds_read_b128 v[192:195], v154 offset:51200
	ds_read_b128 v[196:199], v154 offset:52224
	ds_read_b128 v[200:203], v154 offset:53248
	ds_read_b128 v[204:207], v154 offset:54272
	ds_read_b128 v[208:211], v154 offset:55296
	ds_read_b128 v[232:235], v154 offset:56320
	global_load_lds_dwordx4 v[148:149], off
	s_add_i32 m0, s22, 0x2000
	s_add_u32 s22, s48, 0x80080
	v_lshl_add_u64 v[148:149], v[212:213], 0, s[62:63]
	s_addc_u32 s23, s49, 0
	s_add_i32 s24, s25, s16
	global_load_lds_dwordx4 v[148:149], off
	v_lshl_add_u64 v[148:149], s[22:23], 0, v[134:135]
	s_mov_b32 m0, s24
	s_nop 0
	global_load_lds_dwordx4 v[148:149], off
	v_lshl_add_u64 v[148:149], s[22:23], 0, v[130:131]
	s_add_i32 m0, s24, 0x2000
	s_nop 0
	global_load_lds_dwordx4 v[148:149], off
	v_lshl_add_u64 v[148:149], v[236:237], 0, s[62:63]
	s_mov_b32 m0, s69
	s_nop 0
	global_load_lds_dwordx4 v[148:149], off
	v_lshl_add_u64 v[148:149], v[238:239], 0, s[62:63]
	s_mov_b32 m0, s70
	s_nop 0
	global_load_lds_dwordx4 v[148:149], off
	s_waitcnt vmcnt(8)
	s_waitcnt lgkmcnt(0)
	s_barrier
	s_setprio 1
	s_waitcnt lgkmcnt(0)
	v_mfma_f32_16x16x32_bf16 v[62:65], v[144:147], v[184:187], v[62:65]
	v_mfma_f32_16x16x32_bf16 v[46:49], v[144:147], v[192:195], v[46:49]
	v_mfma_f32_16x16x32_bf16 v[30:33], v[144:147], v[200:203], v[30:33]
	v_mfma_f32_16x16x32_bf16 v[14:17], v[144:147], v[208:211], v[14:17]
	v_mfma_f32_16x16x32_bf16 v[62:65], v[156:159], v[188:191], v[62:65]
	v_mfma_f32_16x16x32_bf16 v[46:49], v[156:159], v[196:199], v[46:49]
	v_mfma_f32_16x16x32_bf16 v[30:33], v[156:159], v[204:207], v[30:33]
	v_mfma_f32_16x16x32_bf16 v[14:17], v[156:159], v[232:235], v[14:17]
	v_mfma_f32_16x16x32_bf16 v[58:61], v[160:163], v[184:187], v[58:61]
	v_mfma_f32_16x16x32_bf16 v[42:45], v[160:163], v[192:195], v[42:45]
	v_mfma_f32_16x16x32_bf16 v[26:29], v[160:163], v[200:203], v[26:29]
	v_mfma_f32_16x16x32_bf16 v[10:13], v[160:163], v[208:211], v[10:13]
	v_mfma_f32_16x16x32_bf16 v[58:61], v[164:167], v[188:191], v[58:61]
	v_mfma_f32_16x16x32_bf16 v[42:45], v[164:167], v[196:199], v[42:45]
	v_mfma_f32_16x16x32_bf16 v[26:29], v[164:167], v[204:207], v[26:29]
	v_mfma_f32_16x16x32_bf16 v[10:13], v[164:167], v[232:235], v[10:13]
	s_setprio 0
	s_setprio 1
	v_mfma_f32_16x16x32_bf16 v[54:57], v[168:171], v[184:187], v[54:57]
	v_mfma_f32_16x16x32_bf16 v[38:41], v[168:171], v[192:195], v[38:41]
	v_mfma_f32_16x16x32_bf16 v[22:25], v[168:171], v[200:203], v[22:25]
	v_mfma_f32_16x16x32_bf16 v[6:9], v[168:171], v[208:211], v[6:9]
	v_mfma_f32_16x16x32_bf16 v[54:57], v[172:175], v[188:191], v[54:57]
	v_mfma_f32_16x16x32_bf16 v[38:41], v[172:175], v[196:199], v[38:41]
	v_mfma_f32_16x16x32_bf16 v[22:25], v[172:175], v[204:207], v[22:25]
	v_mfma_f32_16x16x32_bf16 v[6:9], v[172:175], v[232:235], v[6:9]
	v_mfma_f32_16x16x32_bf16 v[50:53], v[176:179], v[184:187], v[50:53]
	v_mfma_f32_16x16x32_bf16 v[34:37], v[176:179], v[192:195], v[34:37]
	v_mfma_f32_16x16x32_bf16 v[18:21], v[176:179], v[200:203], v[18:21]
	v_mfma_f32_16x16x32_bf16 v[2:5], v[176:179], v[208:211], v[2:5]
	v_mfma_f32_16x16x32_bf16 v[50:53], v[180:183], v[188:191], v[50:53]
	v_mfma_f32_16x16x32_bf16 v[34:37], v[180:183], v[196:199], v[34:37]
	v_mfma_f32_16x16x32_bf16 v[18:21], v[180:183], v[204:207], v[18:21]
	v_mfma_f32_16x16x32_bf16 v[2:5], v[180:183], v[232:235], v[2:5]
	s_setprio 0
	s_barrier
	s_add_i32 s21, s21, 2
	s_add_u32 s46, s46, 0x100
	s_addc_u32 s47, s47, 0
	s_add_u32 s19, s19, 0x100
	s_addc_u32 s20, s20, 0
	s_cmp_gt_u32 s21, 29
	s_cbranch_scc0 .LBB0_340
	s_and_b64 vcc, exec, s[8:9]
	s_cbranch_vccz .LBB0_343
	s_barrier
